# 7.12 branch-test shortening: the three wave-uniform ballot tests in the selected-loop dispatch use s_cmp_lg_u64 on the lane mask instead of v_cndmask+v_cmp+vccz
# speedup vs baseline: 1.0022x; 1.0022x over previous
.LBB0_419:
	s_cmp_eq_u32 s13, s12
	s_cbranch_scc1 .LBB0_418
	s_or_b32 s6, s13, s5
	s_ff1_i32_b64 s18, s[8:9]
	s_lshl_b32 s6, s6, 14
	s_and_b32 s6, s6, 0xc000
	s_lshl_b32 s14, s18, 6
	s_add_i32 s13, s6, 0
	s_or_b32 s16, s14, 63
	s_mov_b64 s[6:7], -1
	s_cmp_ge_i32 s16, s1
	v_lshrrev_b64 v[162:163], s18, v[38:39]
	v_lshrrev_b64 v[164:165], s18, v[40:41]
	s_cbranch_scc0 .LBB0_439
	s_cmp_le_i32 s16, s2
	s_cselect_b64 s[6:7], -1, 0
	s_cmp_gt_i32 s14, s4
	v_and_b32_e32 v0, 1, v164
	s_cselect_b64 s[18:19], -1, 0
	v_cmp_eq_u32_e64 s[42:43], 1, v0
	v_and_b32_e32 v0, 1, v162
	s_and_b64 s[18:19], s[6:7], s[18:19]
	v_cmp_eq_u32_e64 s[44:45], 1, v0
	s_andn2_b64 vcc, exec, s[18:19]
	s_or_b64 s[18:19], s[44:45], s[42:43]
	s_mov_b64 s[6:7], -1
	s_cbranch_vccz .LBB0_430
	s_cmp_lg_u64 s[18:19], 0
	s_cbranch_scc0 .Lsel_fast
	v_add_u32_e32 v54, s13, v196
	v_cmp_ne_u32_e32 vcc, 0, v0
	v_sub_u32_e32 v0, s14, v140
	v_add_u32_e32 v62, v54, v194
	v_add_u32_e32 v89, v54, v195
	v_lshl_add_u32 v0, v0, 2, v216
	s_cbranch_vccz .Lp0_skip0
	v_add_u32_e32 v63, 0xffc, v0
	ds_read_b128 v[54:57], v62 offset:16384
	ds_read_b128 v[58:61], v62 offset:18432
	ds_read_b128 v[64:67], v62 offset:20480
	ds_read_b128 v[68:71], v89 offset:16384
	ds_read_b128 v[72:75], v62 offset:22528
	ds_read2_b32 v[90:91], v63 offset1:1
	ds_read2_b32 v[92:93], v63 offset0:2 offset1:3
	ds_read2_b32 v[94:95], v63 offset0:16 offset1:17
	ds_read2_b32 v[96:97], v63 offset0:18 offset1:19
	ds_read2_b32 v[98:99], v63 offset0:32 offset1:33
	ds_read2_b32 v[100:101], v63 offset0:34 offset1:35
	ds_read2_b32 v[154:155], v63 offset0:48 offset1:49
	ds_read2_b32 v[156:157], v63 offset0:50 offset1:51
	s_waitcnt lgkmcnt(8)
	s_setprio 1
	v_mfma_f32_16x16x32_bf16 v[54:57], v[54:57], v[2:5], 0
	v_mfma_f32_16x16x32_bf16 v[58:61], v[58:61], v[2:5], 0
	v_mfma_f32_16x16x32_bf16 v[54:57], v[68:71], v[6:9], v[54:57]
	ds_read_b128 v[68:71], v89 offset:18432
	ds_read_b128 v[76:79], v89 offset:20480
	v_mfma_f32_16x16x32_bf16 v[64:67], v[64:67], v[2:5], 0
	v_mfma_f32_16x16x32_bf16 v[84:87], v[72:75], v[2:5], 0
	s_waitcnt lgkmcnt(0)
	v_mfma_f32_16x16x32_bf16 v[58:61], v[68:71], v[6:9], v[58:61]
	ds_read_b128 v[68:71], v89 offset:22528
	v_mfma_f32_16x16x32_bf16 v[64:67], v[76:79], v[6:9], v[64:67]
	s_waitcnt lgkmcnt(0)
	v_mfma_f32_16x16x32_bf16 v[84:87], v[68:71], v[6:9], v[84:87]
	s_setprio 0
	v_pk_fma_f32 v[54:55], v[54:55], s[36:37], v[90:91] op_sel_hi:[1,0,1]
	v_pk_fma_f32 v[56:57], v[56:57], s[36:37], v[92:93] op_sel_hi:[1,0,1]
	s_nop 1
	v_pk_fma_f32 v[58:59], v[58:59], s[36:37], v[94:95] op_sel_hi:[1,0,1]
	v_pk_fma_f32 v[60:61], v[60:61], s[36:37], v[96:97] op_sel_hi:[1,0,1]
	v_pk_fma_f32 v[64:65], v[64:65], s[36:37], v[98:99] op_sel_hi:[1,0,1]
	v_pk_fma_f32 v[66:67], v[66:67], s[36:37], v[100:101] op_sel_hi:[1,0,1]
	v_pk_fma_f32 v[84:85], v[84:85], s[36:37], v[154:155] op_sel_hi:[1,0,1]
	v_pk_fma_f32 v[86:87], v[86:87], s[36:37], v[156:157] op_sel_hi:[1,0,1]
	v_or_b32_e32 v83, s14, v197
	v_sub_u32_e32 v88, v140, v83
	v_cmp_le_i32_e64 s[6:7], 0, v88
	v_cmp_le_i32_e64 s[18:19], 1, v88
	v_cmp_le_i32_e64 s[98:99], 2, v88
	v_cmp_le_i32_e64 s[100:101], 3, v88
	v_cndmask_b32_e64 v54, v148, v54, s[6:7]
	v_cndmask_b32_e64 v55, v148, v55, s[18:19]
	v_cndmask_b32_e64 v56, v148, v56, s[98:99]
	v_cndmask_b32_e64 v57, v148, v57, s[100:101]
	v_cmp_le_i32_e64 s[6:7], 16, v88
	v_cmp_le_i32_e64 s[18:19], 17, v88
	v_cmp_le_i32_e64 s[98:99], 18, v88
	v_cmp_le_i32_e64 s[100:101], 19, v88
	v_cndmask_b32_e64 v58, v148, v58, s[6:7]
	v_cndmask_b32_e64 v59, v148, v59, s[18:19]
	v_cndmask_b32_e64 v60, v148, v60, s[98:99]
	v_cndmask_b32_e64 v61, v148, v61, s[100:101]
	v_cmp_le_i32_e64 s[6:7], 32, v88
	v_cmp_le_i32_e64 s[18:19], 33, v88
	v_cmp_le_i32_e64 s[98:99], 34, v88
	v_cmp_le_i32_e64 s[100:101], 35, v88
	v_cndmask_b32_e64 v64, v148, v64, s[6:7]
	v_cndmask_b32_e64 v65, v148, v65, s[18:19]
	v_cndmask_b32_e64 v66, v148, v66, s[98:99]
	v_cndmask_b32_e64 v67, v148, v67, s[100:101]
	v_cmp_le_i32_e64 s[6:7], 48, v88
	v_cmp_le_i32_e64 s[18:19], 49, v88
	v_cmp_le_i32_e64 s[98:99], 50, v88
	v_cmp_le_i32_e64 s[100:101], 51, v88
	v_cndmask_b32_e64 v84, v148, v84, s[6:7]
	v_cndmask_b32_e64 v85, v148, v85, s[18:19]
	v_cndmask_b32_e64 v86, v148, v86, s[98:99]
	v_cndmask_b32_e64 v87, v148, v87, s[100:101]
	v_max3_f32 v63, v54, v55, v56
	v_max3_f32 v63, v63, v57, v58
	v_max3_f32 v63, v63, v59, v60
	v_max3_f32 v63, v63, v61, v64
	v_max3_f32 v63, v63, v65, v66
	v_max3_f32 v63, v63, v67, v84
	v_max3_f32 v63, v63, v85, v86
	v_max3_f32 v63, v63, v87, s29
	v_mov_b32_e32 v68, v63
	s_nop 1
	v_permlane16_swap_b32_e32 v63, v68
	v_max_f32_e32 v63, v63, v68
	v_mov_b32_e32 v68, v63
	s_nop 1
	v_permlane32_swap_b32_e32 v63, v68
	v_max_f32_e32 v63, v63, v68
	v_cndmask_b32_e64 v63, v148, v63, s[44:45]
	v_max_f32_e32 v68, v160, v63
	v_sub_f32_e32 v69, v160, v68
	v_exp_f32_e32 v70, v69
	v_cndmask_b32_e64 v82, v209, v68, s[44:45]
	v_mov_b32_e32 v160, v68
	v_pk_mul_f32 v[36:37], v[36:37], v[70:71] op_sel_hi:[1,0]
	v_pk_mul_f32 v[34:35], v[34:35], v[70:71] op_sel_hi:[1,0]
	v_pk_mul_f32 v[48:49], v[48:49], v[70:71] op_sel_hi:[1,0]
	v_pk_mul_f32 v[46:47], v[46:47], v[70:71] op_sel_hi:[1,0]
	v_pk_mul_f32 v[44:45], v[44:45], v[70:71] op_sel_hi:[1,0]
	v_pk_mul_f32 v[42:43], v[42:43], v[70:71] op_sel_hi:[1,0]
	v_pk_mul_f32 v[52:53], v[52:53], v[70:71] op_sel_hi:[1,0]
	v_pk_mul_f32 v[50:51], v[50:51], v[70:71] op_sel_hi:[1,0]
	v_pk_add_f32 v[54:55], v[54:55], v[82:83] op_sel_hi:[1,0] neg_lo:[0,1] neg_hi:[0,1]
	v_pk_add_f32 v[56:57], v[56:57], v[82:83] op_sel_hi:[1,0] neg_lo:[0,1] neg_hi:[0,1]
	v_pk_add_f32 v[58:59], v[58:59], v[82:83] op_sel_hi:[1,0] neg_lo:[0,1] neg_hi:[0,1]
	v_pk_add_f32 v[60:61], v[60:61], v[82:83] op_sel_hi:[1,0] neg_lo:[0,1] neg_hi:[0,1]
	v_pk_add_f32 v[64:65], v[64:65], v[82:83] op_sel_hi:[1,0] neg_lo:[0,1] neg_hi:[0,1]
	v_pk_add_f32 v[66:67], v[66:67], v[82:83] op_sel_hi:[1,0] neg_lo:[0,1] neg_hi:[0,1]
	v_pk_add_f32 v[84:85], v[84:85], v[82:83] op_sel_hi:[1,0] neg_lo:[0,1] neg_hi:[0,1]
	v_pk_add_f32 v[86:87], v[86:87], v[82:83] op_sel_hi:[1,0] neg_lo:[0,1] neg_hi:[0,1]
	v_exp_f32_e32 v54, v54
	v_exp_f32_e32 v55, v55
	v_exp_f32_e32 v56, v56
	v_exp_f32_e32 v57, v57
	v_exp_f32_e32 v58, v58
	v_exp_f32_e32 v59, v59
	v_exp_f32_e32 v60, v60
	v_exp_f32_e32 v61, v61
	v_exp_f32_e32 v64, v64
	v_exp_f32_e32 v65, v65
	v_exp_f32_e32 v66, v66
	v_exp_f32_e32 v67, v67
	v_exp_f32_e32 v84, v84
	v_exp_f32_e32 v85, v85
	v_exp_f32_e32 v86, v86
	v_exp_f32_e32 v87, v87
	s_nop 0
	v_pk_add_f32 v[72:73], v[54:55], v[56:57]
	v_pk_add_f32 v[74:75], v[58:59], v[60:61]
	v_pk_add_f32 v[76:77], v[64:65], v[66:67]
	v_pk_add_f32 v[78:79], v[84:85], v[86:87]
	v_pk_add_f32 v[72:73], v[72:73], v[74:75]
	v_pk_add_f32 v[76:77], v[76:77], v[78:79]
	s_nop 0
	v_pk_add_f32 v[72:73], v[72:73], v[76:77]
	s_nop 0
	v_add_f32_e32 v72, v72, v73
	v_fma_f32 v144, v144, v70, v72
	v_cvt_pk_bf16_f32 v61, v60, v61
	v_cvt_pk_bf16_f32 v60, v58, v59
	v_cvt_pk_bf16_f32 v59, v56, v57
	v_cvt_pk_bf16_f32 v58, v54, v55
	v_cvt_pk_bf16_f32 v54, v64, v65
	v_cvt_pk_bf16_f32 v55, v66, v67
	v_cvt_pk_bf16_f32 v56, v84, v85
	v_cvt_pk_bf16_f32 v57, v86, v87
	v_cndmask_b32_e64 v63, 0, 1, s[42:43]
	v_cmp_ne_u32_e32 vcc, 0, v63
	s_cbranch_vccz .LBB0_445

.LBB0_430:
	s_andn2_b64 vcc, exec, s[6:7]
	s_cbranch_vccnz .LBB0_438
	s_cmp_lg_u64 s[18:19], 0
	s_cbranch_scc0 .Lsel_fast
	v_add_u32_e32 v54, s13, v196
	v_sub_u32_e32 v0, s14, v140
	v_add_u32_e32 v62, v54, v194
	v_add_u32_e32 v89, v54, v195
	v_lshl_add_u32 v0, v0, 2, v216
	s_cmp_lg_u64 s[44:45], 0
	s_movk_i32 s98, 0xfec
	s_cselect_b32 s98, 0xffc, s98
	v_add_u32_e32 v230, s98, v0
	v_add_u32_e32 v231, 0xfec, v0
	ds_read_b128 v[64:67], v62 offset:16384
	ds_read_b128 v[54:57], v89 offset:16384
	ds_read_b128 v[68:71], v62 offset:18432
	ds_read_b128 v[58:61], v89 offset:18432
	ds_read_b128 v[72:75], v62 offset:20480
	ds_read_b128 v[76:79], v89 offset:20480
	ds_read_b128 v[80:83], v62 offset:22528
	ds_read_b128 v[84:87], v89 offset:22528
	ds_read2_b32 v[90:91], v230 offset1:1
	ds_read2_b32 v[92:93], v230 offset0:2 offset1:3
	ds_read2_b32 v[94:95], v230 offset0:16 offset1:17
	ds_read2_b32 v[96:97], v230 offset0:18 offset1:19
	s_waitcnt lgkmcnt(4)
	ds_read2_b32 v[98:99], v230 offset0:32 offset1:33
	ds_read2_b32 v[100:101], v230 offset0:34 offset1:35
	ds_read2_b32 v[154:155], v230 offset0:48 offset1:49
	ds_read2_b32 v[156:157], v230 offset0:50 offset1:51
	s_cbranch_scc0 .Lp1v_m1
	s_cmp_lg_u64 s[42:43], 0
	s_cbranch_scc0 .Lp1v_only0
	s_setprio 1
	v_mfma_f32_16x16x32_bf16 v[170:173], v[64:67], v[2:5], 0
	v_mfma_f32_16x16x32_bf16 v[174:177], v[68:71], v[2:5], 0
	v_mfma_f32_16x16x32_bf16 v[170:173], v[54:57], v[6:9], v[170:173]
	v_mfma_f32_16x16x32_bf16 v[178:181], v[72:75], v[2:5], 0
	v_mfma_f32_16x16x32_bf16 v[174:177], v[58:61], v[6:9], v[174:177]
	v_mfma_f32_16x16x32_bf16 v[182:185], v[80:83], v[2:5], 0
	v_mfma_f32_16x16x32_bf16 v[178:181], v[76:79], v[6:9], v[178:181]
	v_mfma_f32_16x16x32_bf16 v[182:185], v[84:87], v[6:9], v[182:185]
	v_mfma_f32_16x16x32_bf16 v[64:67], v[64:67], v[10:13], 0
	v_mfma_f32_16x16x32_bf16 v[68:71], v[68:71], v[10:13], 0
	v_mfma_f32_16x16x32_bf16 v[64:67], v[54:57], v[14:17], v[64:67]
	v_mfma_f32_16x16x32_bf16 v[72:75], v[72:75], v[10:13], 0
	v_mfma_f32_16x16x32_bf16 v[68:71], v[58:61], v[14:17], v[68:71]
	v_mfma_f32_16x16x32_bf16 v[80:83], v[80:83], v[10:13], 0
	v_mfma_f32_16x16x32_bf16 v[72:75], v[76:79], v[14:17], v[72:75]
	v_mfma_f32_16x16x32_bf16 v[80:83], v[84:87], v[14:17], v[80:83]
	s_setprio 0
	s_waitcnt lgkmcnt(0)
	v_pk_fma_f32 v[170:171], v[170:171], s[36:37], v[90:91] op_sel_hi:[1,0,1]
	v_pk_fma_f32 v[172:173], v[172:173], s[36:37], v[92:93] op_sel_hi:[1,0,1]
	v_pk_fma_f32 v[174:175], v[174:175], s[36:37], v[94:95] op_sel_hi:[1,0,1]
	v_pk_fma_f32 v[176:177], v[176:177], s[36:37], v[96:97] op_sel_hi:[1,0,1]
	v_pk_fma_f32 v[178:179], v[178:179], s[36:37], v[98:99] op_sel_hi:[1,0,1]
	v_pk_fma_f32 v[180:181], v[180:181], s[36:37], v[100:101] op_sel_hi:[1,0,1]
	v_pk_fma_f32 v[182:183], v[182:183], s[36:37], v[154:155] op_sel_hi:[1,0,1]
	v_pk_fma_f32 v[184:185], v[184:185], s[36:37], v[156:157] op_sel_hi:[1,0,1]
	ds_read2_b32 v[90:91], v231 offset1:1
	ds_read2_b32 v[92:93], v231 offset0:2 offset1:3
	ds_read2_b32 v[94:95], v231 offset0:16 offset1:17
	ds_read2_b32 v[96:97], v231 offset0:18 offset1:19
	ds_read2_b32 v[98:99], v231 offset0:32 offset1:33
	ds_read2_b32 v[100:101], v231 offset0:34 offset1:35
	ds_read2_b32 v[154:155], v231 offset0:48 offset1:49
	ds_read2_b32 v[156:157], v231 offset0:50 offset1:51
	v_max3_f32 v186, v170, v171, v172
	v_max3_f32 v186, v186, v173, v174
	v_max3_f32 v186, v186, v175, v176
	v_max3_f32 v186, v186, v177, v178
	v_max3_f32 v186, v186, v179, v180
	v_max3_f32 v186, v186, v181, v182
	v_max3_f32 v186, v186, v183, v184
	v_max3_f32 v186, v186, v185, s29
	v_mov_b32_e32 v187, v186
	s_nop 1
	v_permlane16_swap_b32_e32 v186, v187
	v_max_f32_e32 v186, v186, v187
	v_mov_b32_e32 v187, v186
	s_nop 1
	v_permlane32_swap_b32_e32 v186, v187
	v_max_f32_e32 v186, v186, v187
	v_cndmask_b32_e64 v186, v148, v186, s[44:45]
	v_max_f32_e32 v187, v160, v186
	s_waitcnt lgkmcnt(0)
	v_pk_fma_f32 v[64:65], v[64:65], s[36:37], v[90:91] op_sel_hi:[1,0,1]
	v_pk_fma_f32 v[66:67], v[66:67], s[36:37], v[92:93] op_sel_hi:[1,0,1]
	v_pk_fma_f32 v[68:69], v[68:69], s[36:37], v[94:95] op_sel_hi:[1,0,1]
	v_pk_fma_f32 v[70:71], v[70:71], s[36:37], v[96:97] op_sel_hi:[1,0,1]
	v_pk_fma_f32 v[72:73], v[72:73], s[36:37], v[98:99] op_sel_hi:[1,0,1]
	v_pk_fma_f32 v[74:75], v[74:75], s[36:37], v[100:101] op_sel_hi:[1,0,1]
	v_pk_fma_f32 v[80:81], v[80:81], s[36:37], v[154:155] op_sel_hi:[1,0,1]
	v_pk_fma_f32 v[82:83], v[82:83], s[36:37], v[156:157] op_sel_hi:[1,0,1]
	v_max3_f32 v76, v64, v65, v66
	v_max3_f32 v76, v76, v67, v68
	v_max3_f32 v76, v76, v69, v70
	v_max3_f32 v76, v76, v71, v72
	v_max3_f32 v76, v76, v73, v74
	v_max3_f32 v76, v76, v75, v80
	v_max3_f32 v76, v76, v81, v82
	v_max3_f32 v76, v76, v83, s29
	v_mov_b32_e32 v77, v76
	s_nop 1
	v_permlane16_swap_b32_e32 v76, v77
	v_max_f32_e32 v76, v76, v77
	v_mov_b32_e32 v77, v76
	s_nop 1
	v_permlane32_swap_b32_e32 v76, v77
	v_max_f32_e32 v76, v76, v77
	v_cndmask_b32_e64 v76, v148, v76, s[42:43]
	v_max_f32_e32 v77, v161, v76
	v_sub_f32_e32 v248, v160, v187
	v_sub_f32_e32 v0, v161, v77
	v_exp_f32_e32 v236, v248
	v_exp_f32_e32 v0, v0
	v_cndmask_b32_e64 v246, v209, v187, s[44:45]
	v_cndmask_b32_e64 v78, v209, v77, s[42:43]
	v_mov_b32_e32 v160, v187
	v_mov_b32_e32 v161, v77
	v_pk_mul_f32 v[36:37], v[36:37], v[236:237] op_sel_hi:[1,0]
	v_pk_mul_f32 v[32:33], v[32:33], v[0:1] op_sel_hi:[1,0]
	v_pk_mul_f32 v[34:35], v[34:35], v[236:237] op_sel_hi:[1,0]
	v_pk_mul_f32 v[30:31], v[30:31], v[0:1] op_sel_hi:[1,0]
	v_pk_mul_f32 v[48:49], v[48:49], v[236:237] op_sel_hi:[1,0]
	v_pk_mul_f32 v[28:29], v[28:29], v[0:1] op_sel_hi:[1,0]
	v_pk_mul_f32 v[46:47], v[46:47], v[236:237] op_sel_hi:[1,0]
	v_pk_mul_f32 v[26:27], v[26:27], v[0:1] op_sel_hi:[1,0]
	v_pk_mul_f32 v[44:45], v[44:45], v[236:237] op_sel_hi:[1,0]
	v_pk_mul_f32 v[24:25], v[24:25], v[0:1] op_sel_hi:[1,0]
	v_pk_mul_f32 v[42:43], v[42:43], v[236:237] op_sel_hi:[1,0]
	v_pk_mul_f32 v[22:23], v[22:23], v[0:1] op_sel_hi:[1,0]
	v_pk_mul_f32 v[52:53], v[52:53], v[236:237] op_sel_hi:[1,0]
	v_pk_mul_f32 v[20:21], v[20:21], v[0:1] op_sel_hi:[1,0]
	v_pk_mul_f32 v[50:51], v[50:51], v[236:237] op_sel_hi:[1,0]
	v_pk_mul_f32 v[18:19], v[18:19], v[0:1] op_sel_hi:[1,0]
	v_pk_add_f32 v[170:171], v[170:171], v[246:247] op_sel_hi:[1,0] neg_lo:[0,1] neg_hi:[0,1]
	v_pk_add_f32 v[64:65], v[64:65], v[78:79] op_sel_hi:[1,0] neg_lo:[0,1] neg_hi:[0,1]
	v_pk_add_f32 v[172:173], v[172:173], v[246:247] op_sel_hi:[1,0] neg_lo:[0,1] neg_hi:[0,1]
	v_pk_add_f32 v[66:67], v[66:67], v[78:79] op_sel_hi:[1,0] neg_lo:[0,1] neg_hi:[0,1]
	v_pk_add_f32 v[174:175], v[174:175], v[246:247] op_sel_hi:[1,0] neg_lo:[0,1] neg_hi:[0,1]
	v_pk_add_f32 v[68:69], v[68:69], v[78:79] op_sel_hi:[1,0] neg_lo:[0,1] neg_hi:[0,1]
	v_pk_add_f32 v[176:177], v[176:177], v[246:247] op_sel_hi:[1,0] neg_lo:[0,1] neg_hi:[0,1]
	v_pk_add_f32 v[70:71], v[70:71], v[78:79] op_sel_hi:[1,0] neg_lo:[0,1] neg_hi:[0,1]
	v_pk_add_f32 v[178:179], v[178:179], v[246:247] op_sel_hi:[1,0] neg_lo:[0,1] neg_hi:[0,1]
	v_pk_add_f32 v[72:73], v[72:73], v[78:79] op_sel_hi:[1,0] neg_lo:[0,1] neg_hi:[0,1]
	v_pk_add_f32 v[180:181], v[180:181], v[246:247] op_sel_hi:[1,0] neg_lo:[0,1] neg_hi:[0,1]
	v_pk_add_f32 v[74:75], v[74:75], v[78:79] op_sel_hi:[1,0] neg_lo:[0,1] neg_hi:[0,1]
	v_pk_add_f32 v[182:183], v[182:183], v[246:247] op_sel_hi:[1,0] neg_lo:[0,1] neg_hi:[0,1]
	v_pk_add_f32 v[80:81], v[80:81], v[78:79] op_sel_hi:[1,0] neg_lo:[0,1] neg_hi:[0,1]
	v_pk_add_f32 v[184:185], v[184:185], v[246:247] op_sel_hi:[1,0] neg_lo:[0,1] neg_hi:[0,1]
	v_pk_add_f32 v[82:83], v[82:83], v[78:79] op_sel_hi:[1,0] neg_lo:[0,1] neg_hi:[0,1]
	v_exp_f32_e32 v170, v170
	v_exp_f32_e32 v64, v64
	v_exp_f32_e32 v171, v171
	v_exp_f32_e32 v65, v65
	v_exp_f32_e32 v172, v172
	v_exp_f32_e32 v66, v66
	v_exp_f32_e32 v173, v173
	v_exp_f32_e32 v67, v67
	v_exp_f32_e32 v174, v174
	v_exp_f32_e32 v68, v68
	v_exp_f32_e32 v175, v175
	v_exp_f32_e32 v69, v69
	v_exp_f32_e32 v176, v176
	v_exp_f32_e32 v70, v70
	v_exp_f32_e32 v177, v177
	v_exp_f32_e32 v71, v71
	v_exp_f32_e32 v178, v178
	v_exp_f32_e32 v72, v72
	v_exp_f32_e32 v179, v179
	v_exp_f32_e32 v73, v73
	v_exp_f32_e32 v180, v180
	v_exp_f32_e32 v74, v74
	v_exp_f32_e32 v181, v181
	v_exp_f32_e32 v75, v75
	v_exp_f32_e32 v182, v182
	v_exp_f32_e32 v80, v80
	v_exp_f32_e32 v183, v183
	v_exp_f32_e32 v81, v81
	v_exp_f32_e32 v184, v184
	v_exp_f32_e32 v82, v82
	v_exp_f32_e32 v185, v185
	v_exp_f32_e32 v83, v83
	v_pk_add_f32 v[238:239], v[170:171], v[172:173]
	v_pk_add_f32 v[84:85], v[64:65], v[66:67]
	v_pk_add_f32 v[240:241], v[174:175], v[176:177]
	v_pk_add_f32 v[86:87], v[68:69], v[70:71]
	v_pk_add_f32 v[242:243], v[178:179], v[180:181]
	v_pk_add_f32 v[76:77], v[72:73], v[74:75]
	v_pk_add_f32 v[244:245], v[182:183], v[184:185]
	v_pk_add_f32 v[78:79], v[80:81], v[82:83]
	v_pk_add_f32 v[238:239], v[238:239], v[240:241]
	v_pk_add_f32 v[84:85], v[84:85], v[86:87]
	v_pk_add_f32 v[242:243], v[242:243], v[244:245]
	v_pk_add_f32 v[76:77], v[76:77], v[78:79]
	v_pk_add_f32 v[238:239], v[238:239], v[242:243]
	v_pk_add_f32 v[84:85], v[84:85], v[76:77]
	v_add_f32_e32 v238, v238, v239
	v_add_f32_e32 v84, v84, v85
	v_fma_f32 v144, v144, v236, v238
	v_fma_f32 v145, v145, v0, v84
	v_cvt_pk_bf16_f32 v58, v170, v171
	v_cvt_pk_bf16_f32 v67, v66, v67
	v_cvt_pk_bf16_f32 v59, v172, v173
	v_cvt_pk_bf16_f32 v66, v64, v65
	v_cvt_pk_bf16_f32 v60, v174, v175
	v_cvt_pk_bf16_f32 v68, v68, v69
	v_cvt_pk_bf16_f32 v61, v176, v177
	v_cvt_pk_bf16_f32 v69, v70, v71
	v_cvt_pk_bf16_f32 v54, v178, v179
	v_cvt_pk_bf16_f32 v62, v72, v73
	v_cvt_pk_bf16_f32 v55, v180, v181
	v_cvt_pk_bf16_f32 v63, v74, v75
	v_cvt_pk_bf16_f32 v56, v182, v183
	v_cvt_pk_bf16_f32 v64, v80, v81
	v_cvt_pk_bf16_f32 v57, v184, v185
	v_cvt_pk_bf16_f32 v65, v82, v83
	s_branch .LBB0_446

.LBB0_439:
	s_andn2_b64 vcc, exec, s[6:7]
	s_cbranch_vccnz .LBB0_448
	v_and_b32_e32 v0, 1, v164
	v_cmp_eq_u32_e64 s[42:43], 1, v0
	v_and_b32_e32 v0, 1, v162
	v_cmp_eq_u32_e64 s[44:45], 1, v0
	s_or_b64 s[6:7], s[44:45], s[42:43]
	s_cmp_lg_u64 s[6:7], 0
	s_cbranch_scc0 .Lsel_fast
	v_add_u32_e32 v54, s13, v196
	v_add_u32_e32 v62, v54, v194
	v_add_u32_e32 v0, v54, v195
	s_cmp_lg_u64 s[44:45], 0
	ds_read_b128 v[64:67], v62 offset:16384
	ds_read_b128 v[54:57], v0 offset:16384
	ds_read_b128 v[68:71], v62 offset:18432
	ds_read_b128 v[58:61], v0 offset:18432
	ds_read_b128 v[72:75], v62 offset:20480
	ds_read_b128 v[76:79], v0 offset:20480
	ds_read_b128 v[80:83], v62 offset:22528
	ds_read_b128 v[84:87], v0 offset:22528
	ds_read_b32 v188, v193
	s_waitcnt lgkmcnt(0)
	s_cbranch_scc0 .Lp2v_m1
	s_cmp_lg_u64 s[42:43], 0
	s_cbranch_scc0 .Lp2v_only0
	s_setprio 1
	v_mfma_f32_16x16x32_bf16 v[170:173], v[64:67], v[2:5], 0
	v_mfma_f32_16x16x32_bf16 v[174:177], v[68:71], v[2:5], 0
	v_mfma_f32_16x16x32_bf16 v[170:173], v[54:57], v[6:9], v[170:173]
	v_mfma_f32_16x16x32_bf16 v[178:181], v[72:75], v[2:5], 0
	v_mfma_f32_16x16x32_bf16 v[174:177], v[58:61], v[6:9], v[174:177]
	v_mfma_f32_16x16x32_bf16 v[182:185], v[80:83], v[2:5], 0
	v_mfma_f32_16x16x32_bf16 v[178:181], v[76:79], v[6:9], v[178:181]
	v_mfma_f32_16x16x32_bf16 v[182:185], v[84:87], v[6:9], v[182:185]
	v_mfma_f32_16x16x32_bf16 v[64:67], v[64:67], v[10:13], 0
	v_mfma_f32_16x16x32_bf16 v[68:71], v[68:71], v[10:13], 0
	v_mfma_f32_16x16x32_bf16 v[64:67], v[54:57], v[14:17], v[64:67]
	v_mfma_f32_16x16x32_bf16 v[72:75], v[72:75], v[10:13], 0
	v_mfma_f32_16x16x32_bf16 v[68:71], v[58:61], v[14:17], v[68:71]
	v_mfma_f32_16x16x32_bf16 v[80:83], v[80:83], v[10:13], 0
	v_mfma_f32_16x16x32_bf16 v[72:75], v[76:79], v[14:17], v[72:75]
	v_mfma_f32_16x16x32_bf16 v[80:83], v[84:87], v[14:17], v[80:83]
	s_setprio 0
	s_nop 7
	v_max3_f32 v186, v170, v171, v172
	v_max3_f32 v76, v64, v65, v66
	v_max3_f32 v186, v186, v173, v174
	v_max3_f32 v76, v76, v67, v68
	v_max3_f32 v186, v186, v175, v176
	v_max3_f32 v76, v76, v69, v70
	v_max3_f32 v186, v186, v177, v178
	v_max3_f32 v76, v76, v71, v72
	v_max3_f32 v186, v186, v179, v180
	v_max3_f32 v76, v76, v73, v74
	v_max3_f32 v186, v186, v181, v182
	v_max3_f32 v76, v76, v75, v80
	v_max3_f32 v186, v186, v183, v184
	v_max3_f32 v76, v76, v81, v82
	v_max_f32_e32 v186, v186, v185
	v_max_f32_e32 v76, v76, v83
	v_mov_b32_e32 v187, v186
	v_mov_b32_e32 v77, v76
	s_nop 0
	v_permlane16_swap_b32_e32 v186, v187
	v_permlane16_swap_b32_e32 v76, v77
	v_max_f32_e32 v186, v186, v187
	v_max_f32_e32 v76, v76, v77
	v_mov_b32_e32 v187, v186
	v_mov_b32_e32 v77, v76
	s_nop 0
	v_permlane32_swap_b32_e32 v186, v187
	v_permlane32_swap_b32_e32 v76, v77
	v_max_f32_e32 v186, v186, v187
	v_max_f32_e32 v76, v76, v77
	v_fma_f32 v186, v186, s36, v188
	v_fma_f32 v76, v76, s36, v188
	v_max_f32_e32 v186, s29, v186
	v_max_f32_e32 v76, s29, v76
	v_cndmask_b32_e64 v186, v148, v186, s[44:45]
	v_cndmask_b32_e64 v76, v148, v76, s[42:43]
	v_max_f32_e32 v187, v160, v186
	v_max_f32_e32 v77, v161, v76
	v_sub_f32_e32 v248, v160, v187
	v_sub_f32_e32 v0, v161, v77
	v_exp_f32_e32 v236, v248
	v_exp_f32_e32 v0, v0
	v_cndmask_b32_e64 v186, v209, v187, s[44:45]
	v_cndmask_b32_e64 v76, v209, v77, s[42:43]
	v_mov_b32_e32 v160, v187
	v_mov_b32_e32 v161, v77
	v_sub_f32_e32 v246, v188, v186
	v_sub_f32_e32 v78, v188, v76
	v_pk_mul_f32 v[36:37], v[36:37], v[236:237] op_sel_hi:[1,0]
	v_pk_mul_f32 v[32:33], v[32:33], v[0:1] op_sel_hi:[1,0]
	v_pk_mul_f32 v[34:35], v[34:35], v[236:237] op_sel_hi:[1,0]
	v_pk_mul_f32 v[30:31], v[30:31], v[0:1] op_sel_hi:[1,0]
	v_pk_mul_f32 v[48:49], v[48:49], v[236:237] op_sel_hi:[1,0]
	v_pk_mul_f32 v[28:29], v[28:29], v[0:1] op_sel_hi:[1,0]
	v_pk_mul_f32 v[46:47], v[46:47], v[236:237] op_sel_hi:[1,0]
	v_pk_mul_f32 v[26:27], v[26:27], v[0:1] op_sel_hi:[1,0]
	v_pk_mul_f32 v[44:45], v[44:45], v[236:237] op_sel_hi:[1,0]
	v_pk_mul_f32 v[24:25], v[24:25], v[0:1] op_sel_hi:[1,0]
	v_pk_mul_f32 v[42:43], v[42:43], v[236:237] op_sel_hi:[1,0]
	v_pk_mul_f32 v[22:23], v[22:23], v[0:1] op_sel_hi:[1,0]
	v_pk_mul_f32 v[52:53], v[52:53], v[236:237] op_sel_hi:[1,0]
	v_pk_mul_f32 v[20:21], v[20:21], v[0:1] op_sel_hi:[1,0]
	v_pk_mul_f32 v[50:51], v[50:51], v[236:237] op_sel_hi:[1,0]
	v_pk_mul_f32 v[18:19], v[18:19], v[0:1] op_sel_hi:[1,0]
	v_pk_fma_f32 v[170:171], v[170:171], s[36:37], v[246:247] op_sel_hi:[1,0,0]
	v_pk_fma_f32 v[64:65], v[64:65], s[36:37], v[78:79] op_sel_hi:[1,0,0]
	v_pk_fma_f32 v[172:173], v[172:173], s[36:37], v[246:247] op_sel_hi:[1,0,0]
	v_pk_fma_f32 v[66:67], v[66:67], s[36:37], v[78:79] op_sel_hi:[1,0,0]
	v_pk_fma_f32 v[174:175], v[174:175], s[36:37], v[246:247] op_sel_hi:[1,0,0]
	v_pk_fma_f32 v[68:69], v[68:69], s[36:37], v[78:79] op_sel_hi:[1,0,0]
	v_pk_fma_f32 v[176:177], v[176:177], s[36:37], v[246:247] op_sel_hi:[1,0,0]
	v_pk_fma_f32 v[70:71], v[70:71], s[36:37], v[78:79] op_sel_hi:[1,0,0]
	v_pk_fma_f32 v[178:179], v[178:179], s[36:37], v[246:247] op_sel_hi:[1,0,0]
	v_pk_fma_f32 v[72:73], v[72:73], s[36:37], v[78:79] op_sel_hi:[1,0,0]
	v_pk_fma_f32 v[180:181], v[180:181], s[36:37], v[246:247] op_sel_hi:[1,0,0]
	v_pk_fma_f32 v[74:75], v[74:75], s[36:37], v[78:79] op_sel_hi:[1,0,0]
	v_pk_fma_f32 v[182:183], v[182:183], s[36:37], v[246:247] op_sel_hi:[1,0,0]
	v_pk_fma_f32 v[80:81], v[80:81], s[36:37], v[78:79] op_sel_hi:[1,0,0]
	v_pk_fma_f32 v[184:185], v[184:185], s[36:37], v[246:247] op_sel_hi:[1,0,0]
	v_pk_fma_f32 v[82:83], v[82:83], s[36:37], v[78:79] op_sel_hi:[1,0,0]
	v_exp_f32_e32 v170, v170
	v_exp_f32_e32 v64, v64
	v_exp_f32_e32 v171, v171
	v_exp_f32_e32 v65, v65
	v_exp_f32_e32 v172, v172
	v_exp_f32_e32 v66, v66
	v_exp_f32_e32 v173, v173
	v_exp_f32_e32 v67, v67
	v_exp_f32_e32 v174, v174
	v_exp_f32_e32 v68, v68
	v_exp_f32_e32 v175, v175
	v_exp_f32_e32 v69, v69
	v_exp_f32_e32 v176, v176
	v_exp_f32_e32 v70, v70
	v_exp_f32_e32 v177, v177
	v_exp_f32_e32 v71, v71
	v_exp_f32_e32 v178, v178
	v_exp_f32_e32 v72, v72
	v_exp_f32_e32 v179, v179
	v_exp_f32_e32 v73, v73
	v_exp_f32_e32 v180, v180
	v_exp_f32_e32 v74, v74
	v_exp_f32_e32 v181, v181
	v_exp_f32_e32 v75, v75
	v_exp_f32_e32 v182, v182
	v_exp_f32_e32 v80, v80
	v_exp_f32_e32 v183, v183
	v_exp_f32_e32 v81, v81
	v_exp_f32_e32 v184, v184
	v_exp_f32_e32 v82, v82
	v_exp_f32_e32 v185, v185
	v_exp_f32_e32 v83, v83
	v_pk_add_f32 v[238:239], v[170:171], v[172:173]
	v_pk_add_f32 v[84:85], v[64:65], v[66:67]
	v_pk_add_f32 v[240:241], v[174:175], v[176:177]
	v_pk_add_f32 v[86:87], v[68:69], v[70:71]
	v_pk_add_f32 v[242:243], v[178:179], v[180:181]
	v_pk_add_f32 v[76:77], v[72:73], v[74:75]
	v_pk_add_f32 v[244:245], v[182:183], v[184:185]
	v_pk_add_f32 v[78:79], v[80:81], v[82:83]
	v_pk_add_f32 v[238:239], v[238:239], v[240:241]
	v_pk_add_f32 v[84:85], v[84:85], v[86:87]
	v_pk_add_f32 v[242:243], v[242:243], v[244:245]
	v_pk_add_f32 v[76:77], v[76:77], v[78:79]
	v_pk_add_f32 v[238:239], v[238:239], v[242:243]
	v_pk_add_f32 v[84:85], v[84:85], v[76:77]
	v_add_f32_e32 v238, v238, v239
	v_add_f32_e32 v84, v84, v85
	v_fma_f32 v144, v144, v236, v238
	v_fma_f32 v145, v145, v0, v84
	v_cvt_pk_bf16_f32 v58, v170, v171
	v_cvt_pk_bf16_f32 v67, v66, v67
	v_cvt_pk_bf16_f32 v59, v172, v173
	v_cvt_pk_bf16_f32 v66, v64, v65
	v_cvt_pk_bf16_f32 v60, v174, v175
	v_cvt_pk_bf16_f32 v68, v68, v69
	v_cvt_pk_bf16_f32 v61, v176, v177
	v_cvt_pk_bf16_f32 v69, v70, v71
	v_cvt_pk_bf16_f32 v54, v178, v179
	v_cvt_pk_bf16_f32 v62, v72, v73
	v_cvt_pk_bf16_f32 v55, v180, v181
	v_cvt_pk_bf16_f32 v63, v74, v75
	v_cvt_pk_bf16_f32 v56, v182, v183
	v_cvt_pk_bf16_f32 v64, v80, v81
	v_cvt_pk_bf16_f32 v57, v184, v185
	v_cvt_pk_bf16_f32 v65, v82, v83
	s_branch .LBB0_446
